# ret_r1/ret_r3 transposed LDS images swizzled, rwkv_prep shift_mu loads batched
# speedup vs baseline: 1.0069x; 1.0069x over previous
.LBB0_892:
	s_and_b32 s31, s26, 31
	s_ashr_i32 s30, s26, 7
	s_lshl_b32 s0, s30, 12
	s_lshl_b32 s1, s31, 7
	s_or_b32 s27, s0, s1
	s_lshl_b32 s28, s29, 7
	s_waitcnt vmcnt(5)
	v_lshlrev_b32_e32 v5, 3, v80
	s_lshl_b32 s0, s29, 8
	v_and_b32_e32 v2, 56, v5
	s_add_u32 s6, s18, s0
	v_ashrrev_i32_e32 v122, 3, v80
	s_addc_u32 s7, s19, 0
	v_lshlrev_b32_e32 v144, 1, v2
	v_add_u32_e32 v0, s27, v122
	s_waitcnt vmcnt(2)
	v_lshl_add_u64 v[16:17], s[6:7], 0, v[144:145]
	v_ashrrev_i32_e32 v1, 31, v0
	v_lshlrev_b32_e32 v2, 2, v2
	v_mov_b32_e32 v3, v145
	v_mad_i64_i32 v[18:19], s[0:1], v0, s62, v[16:17]
	s_waitcnt vmcnt(1)
	v_lshl_add_u64 v[20:21], s[12:13], 0, v[2:3]
	v_lshlrev_b64 v[0:1], 8, v[0:1]
	v_lshl_add_u64 v[22:23], s[14:15], 0, v[2:3]
	v_lshl_add_u64 v[2:3], v[20:21], 0, v[0:1]
	global_load_dwordx4 v[56:59], v[18:19], off offset:2048
	global_load_dwordx4 v[60:63], v[18:19], off offset:2176
	v_lshl_add_u64 v[0:1], v[22:23], 0, v[0:1]
	global_load_dwordx4 v[32:35], v[2:3], off
	global_load_dwordx4 v[40:43], v[0:1], off
	global_load_dwordx4 v[48:51], v[2:3], off offset:16
	global_load_dwordx4 v[52:55], v[0:1], off offset:16
	v_add_u32_e32 v4, 0x200, v80
	v_add_u32_e32 v6, 0x400, v80
	v_add_u32_e32 v8, 0x600, v80
	v_ashrrev_i32_e32 v132, 3, v4
	v_ashrrev_i32_e32 v81, 31, v80
	v_and_b32_e32 v99, 0x78, v5
	v_ashrrev_i32_e32 v5, 31, v4
	v_ashrrev_i32_e32 v7, 31, v6
	v_ashrrev_i32_e32 v9, 31, v8
	s_waitcnt vmcnt(6)
	v_add_u32_e32 v26, s27, v132
	v_ashrrev_i32_e32 v98, 4, v4
	v_ashrrev_i32_e32 v97, 4, v6
	v_lshl_add_u64 v[10:11], v[80:81], 4, s[16:17]
	v_lshl_add_u64 v[4:5], v[4:5], 4, s[16:17]
	v_lshl_add_u64 v[6:7], v[6:7], 4, s[16:17]
	v_lshl_add_u64 v[24:25], v[8:9], 4, s[16:17]
	v_ashrrev_i32_e32 v27, 31, v26
	v_mov_b32_e32 v83, v145
	v_ashrrev_i32_e32 v96, 4, v8
	v_lshlrev_b32_e32 v82, 1, v99
	global_load_dwordx4 v[0:3], v[10:11], off
	global_load_dwordx4 v[12:15], v[4:5], off
	s_nop 0
	global_load_dwordx4 v[8:11], v[6:7], off
	s_nop 0
	global_load_dwordx4 v[4:7], v[24:25], off
	v_lshlrev_b64 v[24:25], 8, v[26:27]
	v_lshl_add_u64 v[28:29], s[6:7], 0, v[82:83]
	v_mad_i64_i32 v[16:17], s[0:1], v26, s62, v[16:17]
	v_lshl_add_u64 v[26:27], v[20:21], 0, v[24:25]
	v_lshl_add_u64 v[44:45], v[22:23], 0, v[24:25]
	v_lshl_add_u64 v[64:65], v[28:29], 0, s[84:85]
	global_load_dwordx4 v[100:103], v[16:17], off offset:2048
	global_load_dwordx4 v[104:107], v[16:17], off offset:2176
	global_load_dwordx4 v[72:75], v[18:19], off offset:3072
	global_load_dwordx4 v[76:79], v[18:19], off offset:3200
	global_load_dwordx4 v[20:23], v[16:17], off offset:3072
	global_load_dwordx4 v[28:31], v[16:17], off offset:3200
	s_nop 0
	global_load_dwordx4 v[16:19], v[26:27], off offset:16
	global_load_dwordx4 v[36:39], v[26:27], off
	s_nop 0
	global_load_dwordx4 v[24:27], v[44:45], off offset:16
	s_nop 0
	global_load_dwordx4 v[44:47], v[44:45], off
	v_ashrrev_i32_e32 v95, 4, v80
	v_add_u32_e32 v66, s27, v95
	v_add_u32_e32 v68, s27, v98
	v_add_u32_e32 v69, s27, v97
	v_add_u32_e32 v70, s27, v96
	v_mad_i64_i32 v[66:67], s[0:1], v66, s62, v[64:65]
	v_mad_i64_i32 v[108:109], s[0:1], v68, s62, v[64:65]
	v_mad_i64_i32 v[110:111], s[0:1], v69, s62, v[64:65]
	v_mad_i64_i32 v[112:113], s[0:1], v70, s62, v[64:65]
	v_bfe_u32 v85, v80, 4, 2
	v_add_u32_e32 v84, 0, v144
	s_add_i32 s34, 0, 0x11000
	s_waitcnt vmcnt(19)
	v_lshlrev_b32_e32 v64, 16, v56
	s_waitcnt vmcnt(18)
	v_lshlrev_b32_e32 v65, 16, v60
	s_waitcnt vmcnt(17)
	v_mov_b32_e32 v86, v32
	s_waitcnt vmcnt(16)
	v_mov_b32_e32 v87, v40
	v_mov_b32_e32 v88, v40
	v_mov_b32_e32 v89, v32
	v_pk_mul_f32 v[68:69], v[86:87], v[64:65]
	v_pk_mul_f32 v[64:65], v[88:89], v[64:65]
	v_mov_b32_e32 v40, v33
	v_add_f32_e32 v83, v65, v64
	v_and_b32_e32 v65, 0xffff0000, v60
	v_and_b32_e32 v64, 0xffff0000, v56
	v_mov_b32_e32 v32, v41
	v_sub_f32_e32 v81, v68, v69
	v_pk_mul_f32 v[68:69], v[40:41], v[64:65]
	v_pk_mul_f32 v[64:65], v[32:33], v[64:65]
	v_mov_b32_e32 v91, v42
	v_add_f32_e32 v124, v65, v64
	v_lshlrev_b32_e32 v65, 16, v61
	v_mov_b32_e32 v92, v42
	v_and_b32_e32 v61, 0xffff0000, v61
	v_and_b32_e32 v60, 0xffff0000, v57
	v_mov_b32_e32 v42, v35
	v_lshlrev_b32_e32 v64, 16, v57
	v_mov_b32_e32 v90, v34
	v_mov_b32_e32 v93, v34
	v_pk_mul_f32 v[56:57], v[42:43], v[60:61]
	v_mov_b32_e32 v34, v43
	v_sub_f32_e32 v127, v56, v57
	v_pk_mul_f32 v[56:57], v[34:35], v[60:61]
	s_waitcnt vmcnt(15)
	v_mov_b32_e32 v114, v48
	v_add_f32_e32 v128, v57, v56
	v_lshlrev_b32_e32 v57, 16, v62
	v_lshlrev_b32_e32 v56, 16, v58
	s_waitcnt vmcnt(14)
	v_mov_b32_e32 v115, v52
	v_mov_b32_e32 v116, v52
	v_mov_b32_e32 v117, v48
	v_pk_mul_f32 v[60:61], v[114:115], v[56:57]
	v_pk_mul_f32 v[56:57], v[116:117], v[56:57]
	v_mov_b32_e32 v52, v49
	v_add_f32_e32 v130, v57, v56
	v_and_b32_e32 v57, 0xffff0000, v62
	v_and_b32_e32 v56, 0xffff0000, v58
	v_mov_b32_e32 v48, v53
	v_sub_f32_e32 v129, v60, v61
	v_pk_mul_f32 v[60:61], v[52:53], v[56:57]
	v_pk_mul_f32 v[56:57], v[48:49], v[56:57]
	v_mov_b32_e32 v118, v50
	v_add_f32_e32 v133, v57, v56
	v_lshlrev_b32_e32 v57, 16, v63
	v_lshlrev_b32_e32 v56, 16, v59
	v_mov_b32_e32 v119, v54
	v_mov_b32_e32 v120, v54
	v_mov_b32_e32 v121, v50
	v_sub_f32_e32 v131, v60, v61
	v_pk_mul_f32 v[60:61], v[118:119], v[56:57]
	v_pk_mul_f32 v[56:57], v[120:121], v[56:57]
	v_mov_b32_e32 v54, v51
	v_add_f32_e32 v135, v57, v56
	v_and_b32_e32 v57, 0xffff0000, v63
	v_and_b32_e32 v56, 0xffff0000, v59
	v_mov_b32_e32 v50, v55
	v_sub_f32_e32 v123, v68, v69
	v_pk_mul_f32 v[68:69], v[90:91], v[64:65]
	v_pk_mul_f32 v[64:65], v[92:93], v[64:65]
	v_pk_mul_f32 v[58:59], v[54:55], v[56:57]
	v_pk_mul_f32 v[56:57], v[50:51], v[56:57]
	v_sub_f32_e32 v125, v68, v69
	v_add_f32_e32 v126, v65, v64
	v_sub_f32_e32 v134, v60, v61
	v_sub_f32_e32 v136, v58, v59
	v_add_f32_e32 v137, v57, v56
	global_load_dwordx4 v[68:71], v[66:67], off
	s_nop 0
	global_load_dwordx4 v[64:67], v[108:109], off
	global_load_dwordx4 v[60:63], v[110:111], off
	global_load_dwordx4 v[56:59], v[112:113], off
	v_cvt_pk_bf16_f32 v108, v81, v123
	v_cvt_pk_bf16_f32 v109, v125, v127
	v_cvt_pk_bf16_f32 v110, v129, v131
	v_cvt_pk_bf16_f32 v111, v134, v136
	v_mad_u64_u32 v[112:113], s[0:1], v122, s65, v[84:85]
	ds_write_b128 v112, v[108:111]
	v_cvt_pk_bf16_f32 v108, v83, v124
	v_cvt_pk_bf16_f32 v109, v126, v128
	v_cvt_pk_bf16_f32 v110, v130, v133
	v_cvt_pk_bf16_f32 v111, v135, v137
	ds_write_b128 v112, v[108:111] offset:128
	s_waitcnt vmcnt(12)
	v_lshlrev_b32_e32 v109, 16, v104
	v_lshlrev_b32_e32 v108, 16, v100
	s_waitcnt vmcnt(6)
	v_mov_b32_e32 v110, v36
	s_waitcnt vmcnt(4)
	v_mov_b32_e32 v111, v44
	v_pk_mul_f32 v[122:123], v[110:111], v[108:109]
	s_nop 0
	v_sub_f32_e32 v81, v122, v123
	v_mov_b32_e32 v122, v44
	v_mov_b32_e32 v123, v36
	v_pk_mul_f32 v[108:109], v[122:123], v[108:109]
	v_mov_b32_e32 v44, v37
	v_add_f32_e32 v83, v109, v108
	v_and_b32_e32 v109, 0xffff0000, v104
	v_and_b32_e32 v108, 0xffff0000, v100
	v_mov_b32_e32 v36, v45
	v_pk_mul_f32 v[124:125], v[44:45], v[108:109]
	v_pk_mul_f32 v[108:109], v[36:37], v[108:109]
	v_sub_f32_e32 v113, v124, v125
	v_add_f32_e32 v133, v109, v108
	v_lshlrev_b32_e32 v109, 16, v105
	v_lshlrev_b32_e32 v108, 16, v101
	v_mov_b32_e32 v124, v38
	v_mov_b32_e32 v125, v46
	v_pk_mul_f32 v[126:127], v[124:125], v[108:109]
	v_and_b32_e32 v105, 0xffff0000, v105
	v_sub_f32_e32 v134, v126, v127
	v_mov_b32_e32 v126, v46
	v_and_b32_e32 v104, 0xffff0000, v101
	v_mov_b32_e32 v46, v39
	v_mov_b32_e32 v127, v38
	v_pk_mul_f32 v[100:101], v[46:47], v[104:105]
	v_mov_b32_e32 v38, v47
	v_sub_f32_e32 v136, v100, v101
	v_pk_mul_f32 v[100:101], v[38:39], v[104:105]
	v_pk_mul_f32 v[108:109], v[126:127], v[108:109]
	v_add_f32_e32 v137, v101, v100
	v_lshlrev_b32_e32 v101, 16, v106
	v_lshlrev_b32_e32 v100, 16, v102
	v_mov_b32_e32 v104, v16
	v_mov_b32_e32 v105, v24
	v_add_f32_e32 v135, v109, v108
	v_pk_mul_f32 v[108:109], v[104:105], v[100:101]
	s_nop 0
	v_sub_f32_e32 v138, v108, v109
	v_mov_b32_e32 v108, v24
	v_mov_b32_e32 v109, v16
	v_pk_mul_f32 v[100:101], v[108:109], v[100:101]
	v_mov_b32_e32 v24, v17
	v_add_f32_e32 v139, v101, v100
	v_and_b32_e32 v101, 0xffff0000, v106
	v_and_b32_e32 v100, 0xffff0000, v102
	v_mov_b32_e32 v16, v25
	v_pk_mul_f32 v[128:129], v[24:25], v[100:101]
	v_pk_mul_f32 v[100:101], v[16:17], v[100:101]
	v_sub_f32_e32 v106, v128, v129
	v_add_f32_e32 v140, v101, v100
	v_lshlrev_b32_e32 v101, 16, v107
	v_lshlrev_b32_e32 v100, 16, v103
	v_mov_b32_e32 v128, v18
	v_mov_b32_e32 v129, v26
	v_pk_mul_f32 v[130:131], v[128:129], v[100:101]
	s_nop 0
	v_sub_f32_e32 v141, v130, v131
	v_mov_b32_e32 v130, v26
	v_mov_b32_e32 v131, v18
	v_pk_mul_f32 v[100:101], v[130:131], v[100:101]
	v_mov_b32_e32 v26, v19
	v_add_f32_e32 v142, v101, v100
	v_and_b32_e32 v101, 0xffff0000, v107
	v_and_b32_e32 v100, 0xffff0000, v103
	v_mov_b32_e32 v18, v27
	v_pk_mul_f32 v[102:103], v[26:27], v[100:101]
	v_pk_mul_f32 v[100:101], v[18:19], v[100:101]
	v_sub_f32_e32 v103, v102, v103
	v_add_f32_e32 v143, v101, v100
	v_cvt_pk_bf16_f32 v100, v81, v113
	v_cvt_pk_bf16_f32 v101, v134, v136
	v_cvt_pk_bf16_f32 v102, v138, v106
	v_mad_u64_u32 v[106:107], s[0:1], v132, s65, v[84:85]
	v_cvt_pk_bf16_f32 v103, v141, v103
	ds_write_b128 v106, v[100:103]
	v_cvt_pk_bf16_f32 v100, v83, v133
	v_cvt_pk_bf16_f32 v101, v135, v137
	v_cvt_pk_bf16_f32 v102, v139, v140
	v_cvt_pk_bf16_f32 v103, v142, v143
	ds_write_b128 v106, v[100:103] offset:128
	v_lshlrev_b32_e32 v101, 16, v76
	v_lshlrev_b32_e32 v100, 16, v72
	v_pk_mul_f32 v[86:87], v[86:87], v[100:101]
	s_nop 0
	v_sub_f32_e32 v81, v86, v87
	v_pk_mul_f32 v[86:87], v[88:89], v[100:101]
	v_mul_f32_e32 v81, 0x3db504f3, v81
	v_add_f32_e32 v83, v87, v86
	v_and_b32_e32 v87, 0xffff0000, v76
	v_and_b32_e32 v86, 0xffff0000, v72
	v_pk_mul_f32 v[32:33], v[32:33], v[86:87]
	v_pk_mul_f32 v[40:41], v[40:41], v[86:87]
	v_add_f32_e32 v32, v33, v32
	v_sub_f32_e32 v40, v40, v41
	v_mul_f32_e32 v76, 0x3db504f3, v32
	v_lshlrev_b32_e32 v33, 16, v77
	v_lshlrev_b32_e32 v32, 16, v73
	v_mul_f32_e32 v72, 0x3db504f3, v40
	v_pk_mul_f32 v[40:41], v[90:91], v[32:33]
	v_pk_mul_f32 v[32:33], v[92:93], v[32:33]
	v_sub_f32_e32 v40, v40, v41
	v_add_f32_e32 v32, v33, v32
	v_mul_f32_e32 v86, 0x3db504f3, v32
	v_and_b32_e32 v33, 0xffff0000, v77
	v_and_b32_e32 v32, 0xffff0000, v73
	v_mul_f32_e32 v84, 0x3db504f3, v40
	v_pk_mul_f32 v[40:41], v[42:43], v[32:33]
	v_pk_mul_f32 v[32:33], v[34:35], v[32:33]
	v_sub_f32_e32 v40, v40, v41
	v_add_f32_e32 v32, v33, v32
	v_mul_f32_e32 v41, 0x3db504f3, v32
	v_lshlrev_b32_e32 v33, 16, v78
	v_lshlrev_b32_e32 v32, 16, v74
	v_pk_mul_f32 v[34:35], v[114:115], v[32:33]
	v_pk_mul_f32 v[32:33], v[116:117], v[32:33]
	v_sub_f32_e32 v34, v34, v35
	v_add_f32_e32 v32, v33, v32
	v_mul_f32_e32 v43, 0x3db504f3, v32
	v_and_b32_e32 v33, 0xffff0000, v78
	v_and_b32_e32 v32, 0xffff0000, v74
	v_mul_f32_e32 v42, 0x3db504f3, v34
	v_pk_mul_f32 v[34:35], v[52:53], v[32:33]
	v_pk_mul_f32 v[32:33], v[48:49], v[32:33]
	v_sub_f32_e32 v34, v34, v35
	v_add_f32_e32 v32, v33, v32
	v_mul_f32_e32 v48, 0x3db504f3, v32
	v_lshlrev_b32_e32 v33, 16, v79
	v_lshlrev_b32_e32 v32, 16, v75
	v_mul_f32_e32 v52, 0x3db504f3, v34
	v_pk_mul_f32 v[34:35], v[118:119], v[32:33]
	v_pk_mul_f32 v[32:33], v[120:121], v[32:33]
	v_sub_f32_e32 v34, v34, v35
	v_add_f32_e32 v32, v33, v32
	v_mul_f32_e32 v53, 0x3db504f3, v32
	v_and_b32_e32 v33, 0xffff0000, v79
	v_and_b32_e32 v32, 0xffff0000, v75
	v_mul_f32_e32 v49, 0x3db504f3, v34
	v_pk_mul_f32 v[34:35], v[54:55], v[32:33]
	v_pk_mul_f32 v[32:33], v[50:51], v[32:33]
	v_sub_f32_e32 v34, v34, v35
	v_add_f32_e32 v32, v33, v32
	v_mul_f32_e32 v40, 0x3db504f3, v40
	v_mul_f32_e32 v35, 0x3db504f3, v34
	v_mul_f32_e32 v50, 0x3db504f3, v32
	v_cvt_pk_bf16_f32 v32, v81, v72
	v_cvt_pk_bf16_f32 v33, v84, v40
	v_mul_f32_e32 v83, 0x3db504f3, v83
	v_cvt_pk_bf16_f32 v34, v42, v52
	v_cvt_pk_bf16_f32 v35, v49, v35
	ds_write_b128 v112, v[32:35] offset:34816
	v_cvt_pk_bf16_f32 v32, v83, v76
	v_cvt_pk_bf16_f32 v33, v86, v41
	v_cvt_pk_bf16_f32 v34, v43, v48
	v_cvt_pk_bf16_f32 v35, v53, v50
	ds_write_b128 v112, v[32:35] offset:34944
	v_lshlrev_b32_e32 v33, 16, v28
	v_lshlrev_b32_e32 v32, 16, v20
	v_pk_mul_f32 v[34:35], v[110:111], v[32:33]
	v_pk_mul_f32 v[32:33], v[122:123], v[32:33]
	v_sub_f32_e32 v34, v34, v35
	v_add_f32_e32 v32, v33, v32
	v_mul_f32_e32 v41, 0x3db504f3, v32
	v_and_b32_e32 v33, 0xffff0000, v28
	v_and_b32_e32 v32, 0xffff0000, v20
	v_mul_f32_e32 v40, 0x3db504f3, v34
	v_pk_mul_f32 v[34:35], v[44:45], v[32:33]
	v_pk_mul_f32 v[32:33], v[36:37], v[32:33]
	v_sub_f32_e32 v20, v34, v35
	v_mul_f32_e32 v42, 0x3db504f3, v20
	v_add_f32_e32 v20, v33, v32
	v_lshlrev_b32_e32 v33, 16, v29
	v_lshlrev_b32_e32 v32, 16, v21
	v_pk_mul_f32 v[34:35], v[124:125], v[32:33]
	v_mul_f32_e32 v36, 0x3db504f3, v20
	v_sub_f32_e32 v20, v34, v35
	v_pk_mul_f32 v[32:33], v[126:127], v[32:33]
	v_mul_f32_e32 v34, 0x3db504f3, v20
	v_add_f32_e32 v20, v33, v32
	v_and_b32_e32 v29, 0xffff0000, v29
	v_and_b32_e32 v28, 0xffff0000, v21
	v_mul_f32_e32 v32, 0x3db504f3, v20
	v_pk_mul_f32 v[20:21], v[46:47], v[28:29]
	v_ashrrev_i32_e32 v73, 2, v80
	v_sub_f32_e32 v20, v20, v21
	v_mul_f32_e32 v33, 0x3db504f3, v20
	v_pk_mul_f32 v[20:21], v[38:39], v[28:29]
	v_lshlrev_b32_e32 v72, 4, v85
	v_add_f32_e32 v20, v21, v20
	v_mul_f32_e32 v35, 0x3db504f3, v20
	v_lshlrev_b32_e32 v21, 16, v30
	v_lshlrev_b32_e32 v20, 16, v22
	v_pk_mul_f32 v[28:29], v[104:105], v[20:21]
	v_pk_mul_f32 v[20:21], v[108:109], v[20:21]
	v_sub_f32_e32 v28, v28, v29
	v_add_f32_e32 v20, v21, v20
	v_mul_f32_e32 v29, 0x3db504f3, v20
	v_and_b32_e32 v21, 0xffff0000, v30
	v_and_b32_e32 v20, 0xffff0000, v22
	v_pk_mul_f32 v[16:17], v[16:17], v[20:21]
	v_pk_mul_f32 v[24:25], v[24:25], v[20:21]
	v_add_f32_e32 v16, v17, v16
	v_sub_f32_e32 v22, v24, v25
	v_mul_f32_e32 v24, 0x3db504f3, v16
	v_lshlrev_b32_e32 v17, 16, v31
	v_lshlrev_b32_e32 v16, 16, v23
	v_pk_mul_f32 v[20:21], v[128:129], v[16:17]
	v_pk_mul_f32 v[16:17], v[130:131], v[16:17]
	v_sub_f32_e32 v20, v20, v21
	v_add_f32_e32 v16, v17, v16
	v_mul_f32_e32 v30, 0x3db504f3, v16
	v_and_b32_e32 v17, 0xffff0000, v31
	v_and_b32_e32 v16, 0xffff0000, v23
	v_mul_f32_e32 v25, 0x3db504f3, v20
	v_pk_mul_f32 v[20:21], v[26:27], v[16:17]
	v_pk_mul_f32 v[16:17], v[18:19], v[16:17]
	v_sub_f32_e32 v20, v20, v21
	v_add_f32_e32 v16, v17, v16
	v_mul_f32_e32 v21, 0x3db504f3, v16
	v_cvt_pk_bf16_f32 v16, v40, v42
	v_mul_f32_e32 v28, 0x3db504f3, v28
	v_mul_f32_e32 v22, 0x3db504f3, v22
	v_mul_f32_e32 v20, 0x3db504f3, v20
	v_cvt_pk_bf16_f32 v17, v34, v33
	v_cvt_pk_bf16_f32 v18, v28, v22
	v_cvt_pk_bf16_f32 v19, v25, v20
	ds_write_b128 v106, v[16:19] offset:34816
	v_cvt_pk_bf16_f32 v16, v41, v36
	v_cvt_pk_bf16_f32 v17, v32, v35
	v_cvt_pk_bf16_f32 v18, v29, v24
	v_cvt_pk_bf16_f32 v19, v30, v21
	ds_write_b128 v106, v[16:19] offset:34944
	v_mov_b32_e32 v16, s34
	v_mad_u32_u24 v16, v99, s65, v16
	v_and_b32_e32 v201, 3, v226
	v_lshlrev_b32_e32 v201, 4, v201
	v_lshl_add_u32 v17, v95, 1, v16
	v_xor_b32_e32 v208, v17, v201
	s_waitcnt vmcnt(3)
	ds_write_b16 v208, v68
	ds_write_b16_d16_hi v208, v68 offset:272
	ds_write_b16 v208, v69 offset:544
	ds_write_b16_d16_hi v208, v69 offset:816
	ds_write_b16 v208, v70 offset:1088
	ds_write_b16_d16_hi v208, v70 offset:1360
	ds_write_b16 v208, v71 offset:1632
	ds_write_b16_d16_hi v208, v71 offset:1904
	v_lshl_add_u32 v17, v98, 1, v16
	v_xor_b32_e32 v209, v17, v201
	s_waitcnt vmcnt(2)
	ds_write_b16 v209, v64
	ds_write_b16_d16_hi v209, v64 offset:272
	ds_write_b16 v209, v65 offset:544
	ds_write_b16_d16_hi v209, v65 offset:816
	ds_write_b16 v209, v66 offset:1088
	ds_write_b16_d16_hi v209, v66 offset:1360
	ds_write_b16 v209, v67 offset:1632
	ds_write_b16_d16_hi v209, v67 offset:1904
	v_lshl_add_u32 v17, v97, 1, v16
	v_xor_b32_e32 v210, v17, v201
	v_lshl_add_u32 v16, v96, 1, v16
	v_xor_b32_e32 v211, v16, v201
	s_waitcnt vmcnt(1)
	ds_write_b16 v210, v60
	ds_write_b16_d16_hi v210, v60 offset:272
	ds_write_b16 v210, v61 offset:544
	ds_write_b16_d16_hi v210, v61 offset:816
	ds_write_b16 v210, v62 offset:1088
	ds_write_b16_d16_hi v210, v62 offset:1360
	ds_write_b16 v210, v63 offset:1632
	ds_write_b16_d16_hi v210, v63 offset:1904
	s_waitcnt vmcnt(0)
	ds_write_b16 v211, v56
	ds_write_b16_d16_hi v211, v56 offset:272
	ds_write_b16 v211, v57 offset:544
	ds_write_b16_d16_hi v211, v57 offset:816
	ds_write_b16 v211, v58 offset:1088
	ds_write_b16_d16_hi v211, v58 offset:1360
	ds_write_b16 v211, v59 offset:1632
	ds_write_b16_d16_hi v211, v59 offset:1904
	v_add_u32_e32 v16, s60, v82
	v_mad_u64_u32 v[18:19], s[0:1], v95, s65, v[16:17]
	ds_write_b128 v18, v[0:3]
	v_mad_u64_u32 v[0:1], s[0:1], v98, s65, v[16:17]
	ds_write_b128 v0, v[12:15]
	v_mad_u64_u32 v[0:1], s[0:1], v97, s65, v[16:17]
	ds_write_b128 v0, v[8:11]
	v_mad_u64_u32 v[0:1], s[0:1], v96, s65, v[16:17]
	ds_write_b128 v0, v[4:7]
	v_bfi_b32 v0, -16, v73, v80
	v_add_u32_e32 v70, 0, v72
	v_mad_u64_u32 v[64:65], s[0:1], v0, s65, v[70:71]
	s_waitcnt lgkmcnt(0)
	s_barrier
	ds_read_b128 v[24:27], v64
	v_and_b32_e32 v65, 15, v80
	v_mul_u32_u24_e32 v71, 0x110, v65
	v_add3_u32 v78, s60, v72, v71
	ds_read_b128 v[0:3], v78
	ds_read_b128 v[32:35], v64 offset:64
	ds_read_b128 v[4:7], v78 offset:64
	ds_read_b128 v[8:11], v78 offset:4352
	ds_read_b128 v[12:15], v78 offset:4416
	ds_read_b128 v[16:19], v78 offset:8704
	ds_read_b128 v[20:23], v78 offset:8768
	ds_read_b128 v[28:31], v78 offset:13056
	ds_read_b128 v[36:39], v78 offset:13120
	s_waitcnt lgkmcnt(8)
	v_mfma_f32_16x16x32_bf16 v[0:3], v[24:27], v[0:3], 0
	ds_read_b128 v[40:43], v78 offset:17408
	ds_read_b128 v[44:47], v78 offset:17472
	ds_read_b128 v[48:51], v78 offset:21760
	ds_read_b128 v[52:55], v78 offset:21824
	ds_read_b128 v[56:59], v78 offset:26112
	ds_read_b128 v[60:63], v78 offset:26176
	s_waitcnt lgkmcnt(11)
	v_mfma_f32_16x16x32_bf16 v[8:11], v[24:27], v[8:11], 0
	ds_read_b128 v[66:69], v78 offset:30464
	ds_read_b128 v[74:77], v78 offset:30528
	v_mad_u32_u24 v70, v65, s65, v70
	s_waitcnt lgkmcnt(9)
	v_mfma_f32_16x16x32_bf16 v[28:31], v[24:27], v[28:31], 0
	v_mfma_f32_16x16x32_bf16 v[0:3], v[32:35], v[4:7], v[0:3]
	v_mfma_f32_16x16x32_bf16 v[4:7], v[32:35], v[12:15], v[8:11]
	s_waitcnt lgkmcnt(8)
	v_mfma_f32_16x16x32_bf16 v[12:15], v[32:35], v[36:39], v[28:31]
	ds_read_b128 v[36:39], v64 offset:128
	v_mfma_f32_16x16x32_bf16 v[16:19], v[24:27], v[16:19], 0
	s_waitcnt lgkmcnt(8)
	v_mfma_f32_16x16x32_bf16 v[40:43], v[24:27], v[40:43], 0
	s_waitcnt lgkmcnt(6)
	v_mfma_f32_16x16x32_bf16 v[48:51], v[24:27], v[48:51], 0
	s_waitcnt lgkmcnt(2)
	v_mfma_f32_16x16x32_bf16 v[66:69], v[24:27], v[66:69], 0
	v_mfma_f32_16x16x32_bf16 v[8:11], v[32:35], v[20:23], v[16:19]
	v_mfma_f32_16x16x32_bf16 v[16:19], v[32:35], v[44:47], v[40:43]
	v_mfma_f32_16x16x32_bf16 v[20:23], v[32:35], v[52:55], v[48:51]
	s_waitcnt lgkmcnt(1)
	v_mfma_f32_16x16x32_bf16 v[40:43], v[32:35], v[74:77], v[66:69]
	ds_read_b128 v[44:47], v78 offset:128
	s_nop 1
	ds_read_b128 v[66:69], v64 offset:192
	ds_read_b128 v[48:51], v78 offset:192
	v_mfma_f32_16x16x32_bf16 v[56:59], v[24:27], v[56:59], 0
	s_waitcnt lgkmcnt(2)
	v_mfma_f32_16x16x32_bf16 v[0:3], v[36:39], v[44:47], v[0:3]
	ds_read_b128 v[44:47], v78 offset:4480
	ds_read_b128 v[52:55], v78 offset:4544
	v_mfma_f32_16x16x32_bf16 v[28:31], v[32:35], v[60:63], v[56:59]
	s_waitcnt lgkmcnt(1)
	v_mfma_f32_16x16x32_bf16 v[4:7], v[36:39], v[44:47], v[4:7]
	ds_read_b128 v[44:47], v78 offset:8832
	ds_read_b128 v[56:59], v78 offset:8896
	s_waitcnt lgkmcnt(1)
	v_mfma_f32_16x16x32_bf16 v[8:11], v[36:39], v[44:47], v[8:11]
	ds_read_b128 v[44:47], v78 offset:13184
	ds_read_b128 v[60:63], v78 offset:13248
	s_waitcnt lgkmcnt(1)
	v_mfma_f32_16x16x32_bf16 v[12:15], v[36:39], v[44:47], v[12:15]
	ds_read_b128 v[44:47], v78 offset:17536
	ds_read_b128 v[74:77], v78 offset:17600
	s_waitcnt lgkmcnt(1)
	v_mfma_f32_16x16x32_bf16 v[86:89], v[36:39], v[44:47], v[16:19]
	s_nop 2
	ds_read_b128 v[16:19], v78 offset:21888
	ds_read_b128 v[90:93], v78 offset:21952
	s_waitcnt lgkmcnt(1)
	v_mfma_f32_16x16x32_bf16 v[96:99], v[36:39], v[16:19], v[20:23]
	ds_read_b128 v[16:19], v78 offset:26240
	ds_read_b128 v[100:103], v78 offset:26304
	s_waitcnt lgkmcnt(1)
	v_mfma_f32_16x16x32_bf16 v[104:107], v[36:39], v[16:19], v[28:31]
	ds_read_b128 v[16:19], v78 offset:30592
	ds_read_b128 v[108:111], v78 offset:30656
	s_waitcnt lgkmcnt(1)
	v_mfma_f32_16x16x32_bf16 v[40:43], v[36:39], v[16:19], v[40:43]
	v_mfma_f32_16x16x32_bf16 v[28:31], v[66:69], v[48:51], v[0:3]
	v_mfma_f32_16x16x32_bf16 v[44:47], v[66:69], v[52:55], v[4:7]
	v_mfma_f32_16x16x32_bf16 v[20:23], v[66:69], v[56:59], v[8:11]
	v_mfma_f32_16x16x32_bf16 v[16:19], v[66:69], v[60:63], v[12:15]
	v_mfma_f32_16x16x32_bf16 v[12:15], v[66:69], v[74:77], v[86:89]
	v_mfma_f32_16x16x32_bf16 v[8:11], v[66:69], v[90:93], v[96:99]
	v_mfma_f32_16x16x32_bf16 v[4:7], v[66:69], v[100:103], v[104:107]
	s_waitcnt lgkmcnt(0)
	v_mfma_f32_16x16x32_bf16 v[0:3], v[66:69], v[108:111], v[40:43]
	s_nop 2
	ds_read_b128 v[40:43], v70 offset:34816
	ds_read_b128 v[48:51], v70 offset:34880
	ds_read_b128 v[52:55], v70 offset:39168
	ds_read_b128 v[56:59], v70 offset:39232
	ds_read_b128 v[60:63], v70 offset:43520
	ds_read_b128 v[74:77], v70 offset:43584
	ds_read_b128 v[86:89], v70 offset:47872
	ds_read_b128 v[90:93], v70 offset:47936
	ds_read_b128 v[96:99], v70 offset:52224
	ds_read_b128 v[100:103], v70 offset:52288
	ds_read_b128 v[104:107], v70 offset:56576
	ds_read_b128 v[108:111], v70 offset:56640
	ds_read_b128 v[112:115], v70 offset:60928
	ds_read_b128 v[116:119], v70 offset:60992
	ds_read_b128 v[120:123], v70 offset:65280
	ds_read_b128 v[124:127], v70 offset:65344
	s_waitcnt lgkmcnt(14)
	v_mfma_f32_16x16x32_bf16 v[40:43], v[24:27], v[40:43], 0
	s_waitcnt lgkmcnt(13)
	v_mfma_f32_16x16x32_bf16 v[52:55], v[24:27], v[52:55], 0
	s_waitcnt lgkmcnt(11)
	v_mfma_f32_16x16x32_bf16 v[60:63], v[24:27], v[60:63], 0
	s_waitcnt lgkmcnt(9)
	v_mfma_f32_16x16x32_bf16 v[86:89], v[24:27], v[86:89], 0
	s_waitcnt lgkmcnt(7)
	v_mfma_f32_16x16x32_bf16 v[96:99], v[24:27], v[96:99], 0
	s_waitcnt lgkmcnt(5)
	v_mfma_f32_16x16x32_bf16 v[104:107], v[24:27], v[104:107], 0
	s_waitcnt lgkmcnt(3)
	v_mfma_f32_16x16x32_bf16 v[112:115], v[24:27], v[112:115], 0
	s_waitcnt lgkmcnt(1)
	v_mfma_f32_16x16x32_bf16 v[24:27], v[24:27], v[120:123], 0
	v_mfma_f32_16x16x32_bf16 v[40:43], v[32:35], v[48:51], v[40:43]
	v_mfma_f32_16x16x32_bf16 v[48:51], v[32:35], v[56:59], v[52:55]
	v_mfma_f32_16x16x32_bf16 v[52:55], v[32:35], v[74:77], v[60:63]
	v_mfma_f32_16x16x32_bf16 v[56:59], v[32:35], v[90:93], v[86:89]
	v_mfma_f32_16x16x32_bf16 v[60:63], v[32:35], v[100:103], v[96:99]
	v_mfma_f32_16x16x32_bf16 v[74:77], v[32:35], v[108:111], v[104:107]
	v_mfma_f32_16x16x32_bf16 v[86:89], v[32:35], v[116:119], v[112:115]
	s_waitcnt lgkmcnt(0)
	v_mfma_f32_16x16x32_bf16 v[24:27], v[32:35], v[124:127], v[24:27]
	ds_read_b128 v[32:35], v70 offset:34944
	ds_read_b128 v[90:93], v70 offset:35008
	s_waitcnt lgkmcnt(1)
	v_mfma_f32_16x16x32_bf16 v[32:35], v[36:39], v[32:35], v[40:43]
	s_nop 2
	ds_read_b128 v[40:43], v70 offset:39296
	ds_read_b128 v[96:99], v70 offset:39360
	s_waitcnt lgkmcnt(1)
	v_mfma_f32_16x16x32_bf16 v[40:43], v[36:39], v[40:43], v[48:51]
	s_nop 2
	ds_read_b128 v[48:51], v70 offset:43648
	ds_read_b128 v[100:103], v70 offset:43712
	s_waitcnt lgkmcnt(1)
	v_mfma_f32_16x16x32_bf16 v[48:51], v[36:39], v[48:51], v[52:55]
	s_nop 2
	ds_read_b128 v[52:55], v70 offset:48000
	ds_read_b128 v[104:107], v70 offset:48064
	s_waitcnt lgkmcnt(1)
	v_mfma_f32_16x16x32_bf16 v[108:111], v[36:39], v[52:55], v[56:59]
	ds_read_b128 v[52:55], v70 offset:52352
	ds_read_b128 v[112:115], v70 offset:52416
	s_waitcnt lgkmcnt(1)
	v_mfma_f32_16x16x32_bf16 v[116:119], v[36:39], v[52:55], v[60:63]
	ds_read_b128 v[52:55], v70 offset:56704
	ds_read_b128 v[120:123], v70 offset:56768
	s_waitcnt lgkmcnt(1)
	v_mfma_f32_16x16x32_bf16 v[74:77], v[36:39], v[52:55], v[74:77]
	ds_read_b128 v[52:55], v70 offset:61056
	ds_read_b128 v[124:127], v70 offset:61120
	s_waitcnt lgkmcnt(1)
	v_mfma_f32_16x16x32_bf16 v[86:89], v[36:39], v[52:55], v[86:89]
	ds_read_b128 v[52:55], v70 offset:65408
	ds_read_b128 v[128:131], v70 offset:65472
	v_and_b32_e32 v70, -16, v73
	s_waitcnt lgkmcnt(0)
	s_waitcnt lgkmcnt(1)
	v_mfma_f32_16x16x32_bf16 v[24:27], v[36:39], v[52:55], v[24:27]
	v_mfma_f32_16x16x32_bf16 v[36:39], v[66:69], v[120:123], v[74:77]
	s_nop 2
	v_lshl_or_b32 v74, v85, 2, v70
	v_or_b32_e32 v75, 1, v74
	v_cvt_f32_i32_e32 v73, v75
	v_or_b32_e32 v76, 2, v74
	v_mfma_f32_16x16x32_bf16 v[60:63], v[66:69], v[90:93], v[32:35]
	v_or_b32_e32 v77, 3, v74
	v_mfma_f32_16x16x32_bf16 v[56:59], v[66:69], v[96:99], v[40:43]
	v_mfma_f32_16x16x32_bf16 v[52:55], v[66:69], v[100:103], v[48:51]
	v_mfma_f32_16x16x32_bf16 v[48:51], v[66:69], v[104:107], v[108:111]
	v_mfma_f32_16x16x32_bf16 v[40:43], v[66:69], v[112:115], v[116:119]
	v_mfma_f32_16x16x32_bf16 v[32:35], v[66:69], v[124:127], v[86:89]
	s_waitcnt lgkmcnt(0)
	v_mfma_f32_16x16x32_bf16 v[24:27], v[66:69], v[128:131], v[24:27]
	v_cvt_f32_i32_e32 v67, v76
	v_mul_f32_e32 v66, v94, v73
	v_cmp_gt_f32_e32 vcc, s75, v66
	v_mul_f32_e32 v69, v94, v67
	s_nop 0
	v_cndmask_b32_e32 v66, 0, v240, vcc
	v_cndmask_b32_e32 v68, 0, v241, vcc
	v_cmp_gt_f32_e32 vcc, s75, v69
	v_fmac_f32_e32 v66, v94, v73
	v_exp_f32_e32 v66, v66
	v_cndmask_b32_e32 v69, 0, v240, vcc
	v_fmac_f32_e32 v69, v94, v67
	v_exp_f32_e32 v67, v69
	v_cvt_f32_i32_e32 v69, v77
	v_add_u32_e32 v73, 4, v74
	v_ldexp_f32 v66, v66, v68
	v_cndmask_b32_e32 v68, 0, v241, vcc
	v_cvt_f32_i32_e32 v73, v73
	v_ldexp_f32 v67, v67, v68
	v_mul_f32_e32 v68, v94, v69
	v_cmp_gt_f32_e32 vcc, s75, v68
	v_pk_mul_f32 v[28:29], v[66:67], v[28:29]
	v_pk_mul_f32 v[44:45], v[66:67], v[44:45]
	v_cndmask_b32_e32 v68, 0, v240, vcc
	v_fmac_f32_e32 v68, v94, v69
	v_mul_f32_e32 v69, v94, v73
	v_cmp_gt_f32_e64 s[6:7], s75, v69
	v_exp_f32_e32 v68, v68
	v_pk_mul_f32 v[20:21], v[66:67], v[20:21]
	v_cndmask_b32_e64 v69, 0, v240, s[6:7]
	v_fmac_f32_e32 v69, v94, v73
	v_exp_f32_e32 v69, v69
	v_cndmask_b32_e32 v73, 0, v241, vcc
	v_ldexp_f32 v68, v68, v73
	v_cndmask_b32_e64 v73, 0, v241, s[6:7]
	v_ldexp_f32 v69, v69, v73
	v_cvt_f32_i32_e32 v73, v74
	v_pk_mul_f32 v[30:31], v[68:69], v[30:31]
	v_pk_mul_f32 v[46:47], v[68:69], v[46:47]
	v_pk_mul_f32 v[22:23], v[68:69], v[22:23]
	v_mul_f32_e32 v78, v94, v73
	v_cmp_gt_f32_e32 vcc, s75, v78
	v_pk_mul_f32 v[18:19], v[68:69], v[18:19]
	v_pk_mul_f32 v[16:17], v[66:67], v[16:17]
	v_cndmask_b32_e32 v78, 0, v240, vcc
	v_fmac_f32_e32 v78, v94, v73
	v_exp_f32_e32 v73, v78
	v_cndmask_b32_e32 v78, 0, v241, vcc
	v_pk_mul_f32 v[14:15], v[68:69], v[14:15]
	v_pk_mul_f32 v[12:13], v[66:67], v[12:13]
	v_ldexp_f32 v78, v73, v78
	v_cvt_f32_ubyte0_e32 v73, v65
	v_mul_f32_e64 v79, v73, -v94
	v_cmp_gt_f32_e32 vcc, s75, v79
	v_pk_mul_f32 v[10:11], v[68:69], v[10:11]
	v_pk_mul_f32 v[8:9], v[66:67], v[8:9]
	v_cndmask_b32_e32 v79, 0, v240, vcc
	v_fma_f32 v73, v73, -v94, v79
	v_exp_f32_e32 v79, v73
	v_or_b32_e32 v73, 16, v65
	v_cvt_f32_ubyte0_e32 v81, v73
	v_mul_f32_e64 v82, v81, -v94
	v_cmp_gt_f32_e64 s[6:7], s75, v82
	v_pk_mul_f32 v[6:7], v[68:69], v[6:7]
	v_pk_mul_f32 v[4:5], v[66:67], v[4:5]
	v_cndmask_b32_e64 v82, 0, v240, s[6:7]
	v_fma_f32 v81, v81, -v94, v82
	v_exp_f32_e32 v81, v81
	v_cndmask_b32_e32 v82, 0, v241, vcc
	v_ldexp_f32 v79, v79, v82
	v_cndmask_b32_e64 v82, 0, v241, s[6:7]
	v_ldexp_f32 v81, v81, v82
	v_or_b32_e32 v82, 32, v65
	v_cvt_f32_ubyte0_e32 v83, v82
	v_mul_f32_e64 v84, v83, -v94
	v_cmp_gt_f32_e32 vcc, s75, v84
	v_pk_mul_f32 v[2:3], v[68:69], v[2:3]
	v_pk_mul_f32 v[0:1], v[66:67], v[0:1]
	v_cndmask_b32_e32 v84, 0, v240, vcc
	v_fma_f32 v83, v83, -v94, v84
	v_or_b32_e32 v84, 48, v65
	v_cvt_f32_ubyte0_e32 v86, v84
	v_mul_f32_e64 v87, v86, -v94
	v_cmp_gt_f32_e64 s[6:7], s75, v87
	v_exp_f32_e32 v83, v83
	s_nop 0
	v_cndmask_b32_e64 v87, 0, v240, s[6:7]
	v_fma_f32 v86, v86, -v94, v87
	v_exp_f32_e32 v86, v86
	v_cndmask_b32_e32 v87, 0, v241, vcc
	v_ldexp_f32 v83, v83, v87
	v_cndmask_b32_e64 v87, 0, v241, s[6:7]
	v_ldexp_f32 v86, v86, v87
	v_or_b32_e32 v87, 64, v65
	v_cvt_f32_ubyte0_e32 v88, v87
	v_mul_f32_e64 v89, v88, -v94
	v_cmp_gt_f32_e32 vcc, s75, v89
	s_nop 1
	v_cndmask_b32_e32 v89, 0, v240, vcc
	v_fma_f32 v88, v88, -v94, v89
	v_or_b32_e32 v89, 0x50, v65
	v_cvt_f32_ubyte0_e32 v90, v89
	v_mul_f32_e64 v91, v90, -v94
	v_cmp_gt_f32_e64 s[6:7], s75, v91
	v_exp_f32_e32 v88, v88
	s_nop 0
	v_cndmask_b32_e64 v91, 0, v240, s[6:7]
	v_fma_f32 v90, v90, -v94, v91
	v_exp_f32_e32 v90, v90
	v_cndmask_b32_e32 v91, 0, v241, vcc
	v_ldexp_f32 v88, v88, v91
	v_cndmask_b32_e64 v91, 0, v241, s[6:7]
	v_ldexp_f32 v90, v90, v91
	v_or_b32_e32 v91, 0x60, v65
	v_cvt_f32_ubyte0_e32 v92, v91
	v_mul_f32_e64 v93, v92, -v94
	v_cmp_gt_f32_e32 vcc, s75, v93
	s_nop 1
	v_cndmask_b32_e32 v93, 0, v240, vcc
	v_fma_f32 v92, v92, -v94, v93
	v_or_b32_e32 v93, 0x70, v65
	v_cvt_f32_ubyte0_e32 v95, v93
	v_mul_f32_e64 v96, v95, -v94
	v_cmp_gt_f32_e64 s[6:7], s75, v96
	v_exp_f32_e32 v92, v92
	s_nop 0
	v_cndmask_b32_e64 v96, 0, v240, s[6:7]
	v_fma_f32 v94, v95, -v94, v96
	v_exp_f32_e32 v94, v94
	v_cndmask_b32_e32 v95, 0, v241, vcc
	v_mul_f32_e32 v96, v78, v79
	v_cmp_ge_i32_e32 vcc, v74, v65
	v_ldexp_f32 v92, v92, v95
	v_cndmask_b32_e64 v95, 0, v241, s[6:7]
	v_cndmask_b32_e32 v96, 0, v96, vcc
	v_mul_f32_e32 v60, v96, v60
	v_ldexp_f32 v94, v94, v95
	v_lshl_add_u32 v95, v65, 1, 0
	v_cvt_pk_bf16_f32 v96, v60, v145
	v_mul_lo_u32 v60, v74, s65
	v_add_u32_e32 v60, v95, v60
	v_mul_f32_e32 v95, v66, v79
	v_cmp_ge_i32_e32 vcc, v75, v65
	ds_write_b16 v60, v96
	s_nop 0
	v_cndmask_b32_e32 v95, 0, v95, vcc
	v_mul_f32_e32 v61, v95, v61
	v_cvt_pk_bf16_f32 v61, v61, v145
	ds_write_b16 v60, v61 offset:272
	v_mul_f32_e32 v61, v67, v79
	v_cmp_ge_i32_e32 vcc, v76, v65
	s_nop 1
	v_cndmask_b32_e32 v61, 0, v61, vcc
	v_mul_f32_e32 v61, v61, v62
	v_cvt_pk_bf16_f32 v61, v61, v145
	ds_write_b16 v60, v61 offset:544
	v_mul_f32_e32 v61, v68, v79
	v_cmp_ge_i32_e32 vcc, v77, v65
	s_nop 1
	v_cndmask_b32_e32 v61, 0, v61, vcc
	v_mul_f32_e32 v61, v61, v63
	v_cvt_pk_bf16_f32 v61, v61, v145
	ds_write_b16 v60, v61 offset:816
	v_mul_f32_e32 v61, v78, v81
	v_cmp_ge_i32_e32 vcc, v74, v73
	s_nop 1
	v_cndmask_b32_e32 v61, 0, v61, vcc
	v_mul_f32_e32 v56, v61, v56
	v_cvt_pk_bf16_f32 v56, v56, v145
	ds_write_b16 v60, v56 offset:32
	v_mul_f32_e32 v56, v66, v81
	v_cmp_ge_i32_e32 vcc, v75, v73
	v_add3_u32 v61, s34, v72, v71
	s_nop 0
	v_cndmask_b32_e32 v56, 0, v56, vcc
	v_mul_f32_e32 v56, v56, v57
	v_cvt_pk_bf16_f32 v56, v56, v145
	ds_write_b16 v60, v56 offset:304
	v_mul_f32_e32 v56, v67, v81
	v_cmp_ge_i32_e32 vcc, v76, v73
	s_nop 1
	v_cndmask_b32_e32 v56, 0, v56, vcc
	v_mul_f32_e32 v56, v56, v58
	v_cvt_pk_bf16_f32 v56, v56, v145
	ds_write_b16 v60, v56 offset:576
	v_mul_f32_e32 v56, v68, v81
	v_cmp_ge_i32_e32 vcc, v77, v73
	s_nop 1
	v_cndmask_b32_e32 v56, 0, v56, vcc
	v_mul_f32_e32 v56, v56, v59
	v_cvt_pk_bf16_f32 v56, v56, v145
	ds_write_b16 v60, v56 offset:848
	v_mul_f32_e32 v56, v78, v83
	v_cmp_ge_i32_e32 vcc, v74, v82
	s_nop 1
	v_cndmask_b32_e32 v56, 0, v56, vcc
	v_mul_f32_e32 v52, v56, v52
	v_cvt_pk_bf16_f32 v52, v52, v145
	ds_write_b16 v60, v52 offset:64
	v_mul_f32_e32 v52, v66, v83
	v_cmp_ge_i32_e32 vcc, v75, v82
	s_nop 1
	v_cndmask_b32_e32 v52, 0, v52, vcc
	v_mul_f32_e32 v52, v52, v53
	v_cvt_pk_bf16_f32 v52, v52, v145
	ds_write_b16 v60, v52 offset:336
	v_mul_f32_e32 v52, v67, v83
	v_cmp_ge_i32_e32 vcc, v76, v82
	s_nop 1
	v_cndmask_b32_e32 v52, 0, v52, vcc
	v_mul_f32_e32 v52, v52, v54
	v_cvt_pk_bf16_f32 v52, v52, v145
	ds_write_b16 v60, v52 offset:608
	v_mul_f32_e32 v52, v68, v83
	v_cmp_ge_i32_e32 vcc, v77, v82
	s_nop 1
	v_cndmask_b32_e32 v52, 0, v52, vcc
	v_mul_f32_e32 v52, v52, v55
	v_cvt_pk_bf16_f32 v52, v52, v145
	ds_write_b16 v60, v52 offset:880
	v_mul_f32_e32 v52, v78, v86
	v_cmp_ge_i32_e32 vcc, v74, v84
	s_nop 1
	v_cndmask_b32_e32 v52, 0, v52, vcc
	v_mul_f32_e32 v48, v52, v48
	v_cvt_pk_bf16_f32 v48, v48, v145
	ds_write_b16 v60, v48 offset:96
	v_mul_f32_e32 v48, v66, v86
	v_cmp_ge_i32_e32 vcc, v75, v84
	s_nop 1
	v_cndmask_b32_e32 v48, 0, v48, vcc
	v_mul_f32_e32 v48, v48, v49
	v_cvt_pk_bf16_f32 v48, v48, v145
	ds_write_b16 v60, v48 offset:368
	v_mul_f32_e32 v48, v67, v86
	v_cmp_ge_i32_e32 vcc, v76, v84
	s_nop 1
	v_cndmask_b32_e32 v48, 0, v48, vcc
	v_mul_f32_e32 v48, v48, v50
	v_cvt_pk_bf16_f32 v48, v48, v145
	ds_write_b16 v60, v48 offset:640
	v_mul_f32_e32 v48, v68, v86
	v_cmp_ge_i32_e32 vcc, v77, v84
	s_nop 1
	v_cndmask_b32_e32 v48, 0, v48, vcc
	v_mul_f32_e32 v48, v48, v51
	v_cvt_pk_bf16_f32 v48, v48, v145
	ds_write_b16 v60, v48 offset:912
	v_mul_f32_e32 v48, v78, v88
	v_cmp_ge_i32_e32 vcc, v74, v87
	s_nop 1
	v_cndmask_b32_e32 v48, 0, v48, vcc
	v_mul_f32_e32 v40, v48, v40
	v_cvt_pk_bf16_f32 v40, v40, v145
	ds_write_b16 v60, v40 offset:128
	v_mul_f32_e32 v40, v66, v88
	v_cmp_ge_i32_e32 vcc, v75, v87
	s_nop 1
	v_cndmask_b32_e32 v40, 0, v40, vcc
	v_mul_f32_e32 v40, v40, v41
	v_cvt_pk_bf16_f32 v40, v40, v145
	ds_write_b16 v60, v40 offset:400
	v_mul_f32_e32 v40, v67, v88
	v_cmp_ge_i32_e32 vcc, v76, v87
	s_nop 1
	v_cndmask_b32_e32 v40, 0, v40, vcc
	v_mul_f32_e32 v40, v40, v42
	v_cvt_pk_bf16_f32 v40, v40, v145
	ds_write_b16 v60, v40 offset:672
	v_mul_f32_e32 v40, v68, v88
	v_cmp_ge_i32_e32 vcc, v77, v87
	s_nop 1
	v_cndmask_b32_e32 v40, 0, v40, vcc
	v_mul_f32_e32 v40, v40, v43
	v_cvt_pk_bf16_f32 v40, v40, v145
	ds_write_b16 v60, v40 offset:944
	v_mul_f32_e32 v40, v78, v90
	v_cmp_ge_i32_e32 vcc, v74, v89
	s_nop 1
	v_cndmask_b32_e32 v40, 0, v40, vcc
	v_mul_f32_e32 v36, v40, v36
	v_cvt_pk_bf16_f32 v36, v36, v145
	ds_write_b16 v60, v36 offset:160
	v_mul_f32_e32 v36, v66, v90
	v_cmp_ge_i32_e32 vcc, v75, v89
	s_nop 1
	v_cndmask_b32_e32 v36, 0, v36, vcc
	v_mul_f32_e32 v36, v36, v37
	v_cvt_pk_bf16_f32 v36, v36, v145
	ds_write_b16 v60, v36 offset:432
	v_mul_f32_e32 v36, v67, v90
	v_cmp_ge_i32_e32 vcc, v76, v89
	s_nop 1
	v_cndmask_b32_e32 v36, 0, v36, vcc
	v_mul_f32_e32 v36, v36, v38
	v_cvt_pk_bf16_f32 v36, v36, v145
	ds_write_b16 v60, v36 offset:704
	v_mul_f32_e32 v36, v68, v90
	v_cmp_ge_i32_e32 vcc, v77, v89
	s_nop 1
	v_cndmask_b32_e32 v36, 0, v36, vcc
	v_mul_f32_e32 v36, v36, v39
	v_cvt_pk_bf16_f32 v36, v36, v145
	ds_write_b16 v60, v36 offset:976
	v_mul_f32_e32 v36, v78, v92
	v_cmp_ge_i32_e32 vcc, v74, v91
	s_nop 1
	v_cndmask_b32_e32 v36, 0, v36, vcc
	v_mul_f32_e32 v32, v36, v32
	v_cvt_pk_bf16_f32 v32, v32, v145
	ds_write_b16 v60, v32 offset:192
	v_mul_f32_e32 v32, v66, v92
	v_cmp_ge_i32_e32 vcc, v75, v91
	s_nop 1
	v_cndmask_b32_e32 v32, 0, v32, vcc
	v_mul_f32_e32 v32, v32, v33
	v_cvt_pk_bf16_f32 v32, v32, v145
	ds_write_b16 v60, v32 offset:464
	v_mul_f32_e32 v32, v67, v92
	v_cmp_ge_i32_e32 vcc, v76, v91
	s_nop 1
	v_cndmask_b32_e32 v32, 0, v32, vcc
	v_mul_f32_e32 v32, v32, v34
	v_cvt_pk_bf16_f32 v32, v32, v145
	ds_write_b16 v60, v32 offset:736
	v_mul_f32_e32 v32, v68, v92
	v_cmp_ge_i32_e32 vcc, v77, v91
	s_nop 1
	v_cndmask_b32_e32 v32, 0, v32, vcc
	v_mul_f32_e32 v32, v32, v35
	v_cvt_pk_bf16_f32 v32, v32, v145
	ds_write_b16 v60, v32 offset:1008
	v_mul_f32_e32 v32, v78, v94
	v_cmp_ge_i32_e32 vcc, v74, v93
	s_nop 1
	v_cndmask_b32_e32 v32, 0, v32, vcc
	v_mul_f32_e32 v24, v32, v24
	v_cvt_pk_bf16_f32 v24, v24, v145
	ds_write_b16 v60, v24 offset:224
	v_mul_f32_e32 v24, v66, v94
	v_cmp_ge_i32_e32 vcc, v75, v93
	s_nop 1
	v_cndmask_b32_e32 v24, 0, v24, vcc
	v_mul_f32_e32 v24, v24, v25
	v_cvt_pk_bf16_f32 v24, v24, v145
	ds_write_b16 v60, v24 offset:496
	v_mul_f32_e32 v24, v67, v94
	v_cmp_ge_i32_e32 vcc, v76, v93
	s_nop 1
	v_cndmask_b32_e32 v24, 0, v24, vcc
	v_mul_f32_e32 v24, v24, v26
	v_cvt_pk_bf16_f32 v24, v24, v145
	ds_write_b16 v60, v24 offset:768
	v_mul_f32_e32 v24, v68, v94
	v_cmp_ge_i32_e32 vcc, v77, v93
	s_nop 1
	v_cndmask_b32_e32 v24, 0, v24, vcc
	v_mul_f32_e32 v24, v24, v27
	v_cvt_pk_bf16_f32 v24, v24, v145
	ds_write_b16 v60, v24 offset:1040
	s_waitcnt lgkmcnt(0)
	v_lshrrev_b32_e32 v204, 3, v226
	v_and_b32_e32 v204, 1, v204
	v_lshrrev_b32_e32 v205, 4, v226
	v_and_b32_e32 v205, 3, v205
	v_xor_b32_e32 v206, v204, v205
	v_sub_u32_e32 v207, v206, v205
	v_lshl_add_u32 v202, v207, 4, v61
	v_xor_b32_e32 v206, 2, v206
	v_sub_u32_e32 v207, v206, v205
	v_lshl_add_u32 v203, v207, 4, v61
	ds_read_b128 v[24:27], v64
	ds_read_b128 v[32:35], v202
	ds_read_b128 v[36:39], v203 offset:4352
	ds_read_b128 v[40:43], v64 offset:64
	ds_read_b128 v[48:51], v202 offset:64
	s_waitcnt lgkmcnt(3)
	v_mfma_f32_16x16x32_bf16 v[28:31], v[24:27], v[32:35], v[28:31]
	ds_read_b128 v[32:35], v202 offset:8704
	ds_read_b128 v[52:55], v203 offset:4416
	v_cmp_gt_u32_e32 vcc, 64, v80
	s_waitcnt lgkmcnt(4)
	v_mfma_f32_16x16x32_bf16 v[36:39], v[24:27], v[36:39], v[44:47]
	s_nop 2
	ds_read_b128 v[44:47], v203 offset:13056
	ds_read_b128 v[56:59], v202 offset:8768
	s_waitcnt lgkmcnt(3)
	v_mfma_f32_16x16x32_bf16 v[20:23], v[24:27], v[32:35], v[20:23]
	ds_read_b128 v[32:35], v202 offset:17408
	ds_read_b128 v[74:77], v203 offset:13120
	s_waitcnt lgkmcnt(3)
	v_mfma_f32_16x16x32_bf16 v[16:19], v[24:27], v[44:47], v[16:19]
	ds_read_b128 v[44:47], v203 offset:21760
	ds_read_b128 v[86:89], v202 offset:17472
	s_waitcnt lgkmcnt(3)
	v_mfma_f32_16x16x32_bf16 v[12:15], v[24:27], v[32:35], v[12:15]
	ds_read_b128 v[32:35], v202 offset:26112
	ds_read_b128 v[90:93], v203 offset:21824
	s_waitcnt lgkmcnt(3)
	v_mfma_f32_16x16x32_bf16 v[8:11], v[24:27], v[44:47], v[8:11]
	ds_read_b128 v[44:47], v203 offset:30464
	ds_read_b128 v[94:97], v202 offset:26176
	s_waitcnt lgkmcnt(3)
	v_mfma_f32_16x16x32_bf16 v[4:7], v[24:27], v[32:35], v[4:7]
	ds_read_b128 v[32:35], v203 offset:30528
	s_waitcnt lgkmcnt(2)
	v_mfma_f32_16x16x32_bf16 v[0:3], v[24:27], v[44:47], v[0:3]
	v_mfma_f32_16x16x32_bf16 v[24:27], v[40:43], v[48:51], v[28:31]
	v_mfma_f32_16x16x32_bf16 v[28:31], v[40:43], v[52:55], v[36:39]
	s_nop 2
	ds_read_b128 v[36:39], v64 offset:128
	v_mfma_f32_16x16x32_bf16 v[20:23], v[40:43], v[56:59], v[20:23]
	v_mfma_f32_16x16x32_bf16 v[16:19], v[40:43], v[74:77], v[16:19]
	v_mfma_f32_16x16x32_bf16 v[12:15], v[40:43], v[86:89], v[12:15]
	v_mfma_f32_16x16x32_bf16 v[8:11], v[40:43], v[90:93], v[8:11]
	s_waitcnt lgkmcnt(2)
	v_mfma_f32_16x16x32_bf16 v[4:7], v[40:43], v[94:97], v[4:7]
	s_waitcnt lgkmcnt(1)
	v_mfma_f32_16x16x32_bf16 v[0:3], v[40:43], v[32:35], v[0:3]
	ds_read_b128 v[32:35], v202 offset:128
	ds_read_b128 v[40:43], v64 offset:192
	ds_read_b128 v[44:47], v202 offset:192
	s_waitcnt lgkmcnt(2)
	v_mfma_f32_16x16x32_bf16 v[24:27], v[36:39], v[32:35], v[24:27]
	ds_read_b128 v[32:35], v203 offset:4480
	ds_read_b128 v[48:51], v203 offset:4544
	s_waitcnt lgkmcnt(1)
	v_mfma_f32_16x16x32_bf16 v[28:31], v[36:39], v[32:35], v[28:31]
	ds_read_b128 v[32:35], v202 offset:8832
	ds_read_b128 v[52:55], v202 offset:8896
	s_waitcnt lgkmcnt(1)
	v_mfma_f32_16x16x32_bf16 v[20:23], v[36:39], v[32:35], v[20:23]
	ds_read_b128 v[32:35], v203 offset:13184
	ds_read_b128 v[56:59], v203 offset:13248
	s_waitcnt lgkmcnt(1)
	v_mfma_f32_16x16x32_bf16 v[32:35], v[36:39], v[32:35], v[16:19]
	s_nop 2
	ds_read_b128 v[16:19], v202 offset:17536
	ds_read_b128 v[66:69], v202 offset:17600
	s_waitcnt lgkmcnt(1)
	v_mfma_f32_16x16x32_bf16 v[12:15], v[36:39], v[16:19], v[12:15]
	ds_read_b128 v[16:19], v203 offset:21888
	ds_read_b128 v[74:77], v203 offset:21952
	s_waitcnt lgkmcnt(1)
	v_mfma_f32_16x16x32_bf16 v[8:11], v[36:39], v[16:19], v[8:11]
	ds_read_b128 v[16:19], v202 offset:26240
	ds_read_b128 v[86:89], v202 offset:26304
	s_waitcnt lgkmcnt(1)
	v_mfma_f32_16x16x32_bf16 v[90:93], v[36:39], v[16:19], v[4:7]
	s_nop 2
	ds_read_b128 v[4:7], v203 offset:30592
	ds_read_b128 v[94:97], v203 offset:30656
	s_waitcnt lgkmcnt(1)
	v_mfma_f32_16x16x32_bf16 v[36:39], v[36:39], v[4:7], v[0:3]
	v_mfma_f32_16x16x32_bf16 v[4:7], v[40:43], v[44:47], v[24:27]
	v_mfma_f32_16x16x32_bf16 v[0:3], v[40:43], v[48:51], v[28:31]
	v_mfma_f32_16x16x32_bf16 v[16:19], v[40:43], v[52:55], v[20:23]
	v_mfma_f32_16x16x32_bf16 v[28:31], v[40:43], v[56:59], v[32:35]
	v_mfma_f32_16x16x32_bf16 v[12:15], v[40:43], v[66:69], v[12:15]
	s_nop 1
	v_or_b32_e32 v32, s31, v85
	v_cmp_eq_u32_e64 s[6:7], 0, v32
	s_and_b64 s[0:1], vcc, s[6:7]
	v_mfma_f32_16x16x32_bf16 v[24:27], v[40:43], v[74:77], v[8:11]
	v_mfma_f32_16x16x32_bf16 v[8:11], v[40:43], v[86:89], v[90:93]
	s_waitcnt lgkmcnt(0)
	v_mfma_f32_16x16x32_bf16 v[20:23], v[40:43], v[94:97], v[36:39]
	s_and_saveexec_b64 s[6:7], s[0:1]
	s_cbranch_execz .LBB0_886
	s_lshl_b32 s0, s30, 2
	s_or_b32 s0, s0, s29
	s_ashr_i32 s1, s0, 31
	s_lshl_b64 s[0:1], s[0:1], 2
	s_add_u32 s0, s20, s0
	s_addc_u32 s1, s21, s1
	global_load_dword v20, v145, s[0:1]
	v_mov_b32_e32 v4, s34
	v_add_u32_e32 v0, s34, v71
	v_mad_u32_u24 v4, v73, s65, v4
	v_lshrrev_b32_e32 v212, 3, v226
	v_and_b32_e32 v212, 1, v212
	v_lshlrev_b32_e32 v212, 4, v212
	v_add_u32_e32 v0, v0, v212
	v_add_u32_e32 v4, v4, v212
	ds_read_u16 v0, v0
	ds_read_u16 v8, v4 offset:32
	ds_read_u16 v12, v4 offset:4352
	ds_read_u16 v16, v4 offset:8736
	ds_read_u16 v24, v4 offset:13056
	ds_read_u16 v28, v4 offset:17440
	ds_read_u16 v32, v4 offset:21760
	ds_read_u16 v4, v4 offset:26144
	s_waitcnt lgkmcnt(7)
	v_lshlrev_b32_e32 v0, 16, v0
	s_waitcnt lgkmcnt(6)
	v_lshlrev_b32_e32 v8, 16, v8
	s_waitcnt lgkmcnt(5)
	v_lshlrev_b32_e32 v12, 16, v12
	s_waitcnt lgkmcnt(4)
	v_lshlrev_b32_e32 v33, 16, v16
	s_waitcnt lgkmcnt(3)
	v_lshlrev_b32_e32 v24, 16, v24
	s_waitcnt lgkmcnt(2)
	v_lshlrev_b32_e32 v34, 16, v28
	s_waitcnt lgkmcnt(1)
	v_lshlrev_b32_e32 v32, 16, v32
	s_waitcnt lgkmcnt(0)
	v_lshlrev_b32_e32 v35, 16, v4
	s_waitcnt vmcnt(0)
	v_mul_f32_e32 v4, v20, v0
	v_mul_f32_e32 v0, v20, v8
	v_mul_f32_e32 v16, v20, v12
	v_mul_f32_e32 v28, v20, v33
	v_mul_f32_e32 v12, v20, v24
	v_mul_f32_e32 v24, v20, v34
	v_mul_f32_e32 v8, v20, v32
	v_mul_f32_e32 v20, v20, v35
	s_branch .LBB0_886
